# v7: + residual phases read rows with sc1 loads, barrier skips the L1 invalidate in front of them; placement-robust acquire paths
# speedup vs baseline: 1.0379x; 1.0015x over previous
; #define LAS __attribute__((address_space(3)))
; __global__ void __launch_bounds__(NWAVES * 64, 2) hybrid_fwd(Args args) {
;     ...
;     for (int ph = args.ph_lo; ph < args.ph_hi;) {
;         int tid = threadIdx.x; asm volatile("" : "+v"(tid));
;         const int lane = tid & 63, wave = __builtin_amdgcn_readfirstlane(tid >> 6);
;         const int G = gridDim.x; const int bx = blockIdx.x;
;         unsigned char* ws = args.ws;
;         if (ph == 0) {
;             const int vcu = (G % 8 == 0) ? (bx % 8) * (G / 8) + bx / 8 : bx; const int gw = vcu * NWAVES + wave, NGW = G * NWAVES;
;             LAS float* scr = (LAS float*)(lds + wave * WAVE_SCR);
;             bf16* XN = (bf16*)(ws + WS_XN); bf16* SGW = (bf16*)(ws + WS_SGUW);
.LBB0_7:
	s_or_b64 exec, exec, s[0:1]
	s_load_dwordx2 s[38:39], s[80:81], 0xd0
	s_waitcnt lgkmcnt(0)
	s_cmp_ge_i32 s38, s39
	s_cbranch_scc1 .LBB0_733
	s_add_u32 s0, s80, 0xd8
	s_addc_u32 s1, s81, 0
	v_writelane_b32 v253, s0, 2
	s_add_u32 s56, s34, 0x200000
	s_load_dwordx16 s[8:23], s[80:81], 0x88
	v_writelane_b32 v253, s1, 3
	s_addc_u32 s0, s35, 0
	v_writelane_b32 v253, s0, 4
	s_ashr_i32 s0, s60, 31
	v_writelane_b32 v253, s0, 5
	s_lshr_b32 s0, s0, 29
	s_add_i32 s0, s60, s0
	s_ashr_i32 s3, s0, 3
	s_and_b32 s0, s0, -8
	s_sub_i32 s4, s60, s0
	s_add_u32 s0, s34, 0x100000
	s_addc_u32 s1, s35, 0
	s_add_u32 s62, s34, 0xf700000
	v_writelane_b32 v253, s0, 6
	s_addc_u32 s63, s35, 0
	v_lshrrev_b32_e32 v1, 20, v0
	v_writelane_b32 v253, s1, 7
	s_waitcnt lgkmcnt(0)
	s_add_u32 s0, s22, 0x4dfc000
	v_writelane_b32 v253, s0, 8
	s_addc_u32 s0, s23, 0
	v_writelane_b32 v253, s0, 9
	s_add_u32 s0, s22, 0x423c000
	v_writelane_b32 v253, s0, 10
	s_addc_u32 s0, s23, 0
	v_writelane_b32 v253, s0, 11
	s_add_u32 s0, s22, 0x4e7c000
	v_writelane_b32 v253, s0, 12
	s_addc_u32 s0, s23, 0
	v_writelane_b32 v253, s0, 13
	s_add_u32 s0, s22, 0x4674000
	v_writelane_b32 v253, s0, 14
	s_addc_u32 s0, s23, 0
	s_add_u32 s64, s34, 0x7500000
	s_addc_u32 s65, s35, 0
	v_writelane_b32 v253, s0, 15
	s_add_u32 s0, s22, 0x4df4000
	v_writelane_b32 v253, s0, 16
	s_addc_u32 s0, s23, 0
	v_writelane_b32 v253, s0, 17
	s_add_u32 s0, s22, 0x4200000
	v_writelane_b32 v253, s0, 18
	s_addc_u32 s0, s23, 0
	v_writelane_b32 v253, s0, 19
	s_add_u32 s0, s22, 0x45fc000
	v_writelane_b32 v253, s0, 20
	s_addc_u32 s0, s23, 0
	s_add_u32 s82, s34, 0xfe00000
	s_addc_u32 s83, s35, 0
	s_cmpk_lt_i32 s60, 0x400
	v_writelane_b32 v253, s0, 21
	s_cselect_b64 s[0:1], -1, 0
	v_writelane_b32 v253, s0, 22
	s_cmp_gt_i32 s4, -1
	v_lshrrev_b32_e32 v0, 10, v0
	v_writelane_b32 v253, s1, 23
	s_cselect_b64 s[0:1], -1, 0
	v_writelane_b32 v253, s0, 24
	v_or_b32_e32 v0, v0, v1
	v_mov_b32_e32 v129, 0
	v_writelane_b32 v253, s1, 25
	s_lshl_b32 s0, s4, 7
	s_cmp_eq_u64 s[34:35], 0
	s_cselect_b64 s[6:7], -1, 0
	s_cmp_lg_u64 s[34:35], 0
	v_writelane_b32 v253, s6, 26
	s_cselect_b64 s[66:67], -1, 0
	s_cmpk_lt_i32 s60, 0x200
	v_writelane_b32 v253, s7, 27
	s_cselect_b64 s[6:7], -1, 0
	v_writelane_b32 v253, s6, 28
	s_cmpk_lt_i32 s60, 0x100
	v_mov_b64_e32 v[130:131], 0x400
	v_writelane_b32 v253, s7, 29
	s_cselect_b64 s[6:7], -1, 0
	v_writelane_b32 v253, s6, 30
	v_mov_b64_e32 v[132:133], 0x3ff
	v_mov_b32_e32 v168, 0x358637bd
	v_writelane_b32 v253, s7, 31
	s_add_u32 s6, s34, 0x5400000
	s_addc_u32 s7, s35, 0
	v_writelane_b32 v253, s6, 32
	s_lshl_b32 s1, s60, 9
	s_cmp_gt_i32 s38, -1
	v_writelane_b32 v253, s7, 33
	v_writelane_b32 v253, s1, 34
	s_cselect_b64 s[6:7], -1, 0
	v_writelane_b32 v253, s6, 35
	v_mov_b32_e32 v169, 0x1000
	v_mov_b32_e32 v170, 0x2000
	v_writelane_b32 v253, s7, 36
	s_add_u32 s6, s34, 0x200
	s_addc_u32 s7, s35, 0
	v_writelane_b32 v253, s6, 37
	v_mov_b32_e32 v171, 1
	v_mov_b32_e32 v172, 0x82000
	v_writelane_b32 v253, s7, 38
	s_add_u32 s6, s34, 0x1000
	s_addc_u32 s7, s35, 0
	v_writelane_b32 v253, s6, 39
	v_mov_b32_e32 v173, 0xffffef80
	v_mov_b32_e32 v174, 0xfffff800
	v_writelane_b32 v253, s7, 40
	s_add_u32 s6, s34, 0x1100
	s_addc_u32 s7, s35, 0
	v_writelane_b32 v253, s6, 41
	v_mov_b32_e32 v175, 0x1080
	v_mov_b32_e32 v176, 0xbc800000
	v_writelane_b32 v253, s7, 42
	s_add_u32 s6, s34, 0x1200
	s_addc_u32 s7, s35, 0
	v_writelane_b32 v253, s6, 43
	v_mov_b32_e32 v177, 0x3c800000
	v_mov_b32_e32 v178, 0x3c00
	v_writelane_b32 v253, s7, 44
	s_add_u32 s6, s34, 0x1300
	s_addc_u32 s7, s35, 0
	v_writelane_b32 v253, s6, 45
	v_mov_b32_e32 v179, 0x880
	v_mov_b32_e32 v180, 0x7800
	v_writelane_b32 v253, s7, 46
	s_add_u32 s6, s34, 0x3400
	s_addc_u32 s7, s35, 0
	v_writelane_b32 v253, s6, 47
	v_mov_b32_e32 v181, 0x440000
	v_mov_b32_e32 v182, 0xffc00000
	v_writelane_b32 v253, s7, 48
	s_add_u32 s6, s34, 0x3500
	s_addc_u32 s7, s35, 0
	s_lshl_b32 s1, s60, 8
	v_writelane_b32 v253, s6, 49
	s_and_b32 s1, s1, 0x700
	s_lshl_b32 s2, s60, 6
	v_writelane_b32 v253, s7, 50
	s_add_u32 s1, s34, s1
	v_writelane_b32 v253, s2, 51
	s_addc_u32 s2, s35, 0
	s_add_u32 s6, s1, 0x9000
	s_addc_u32 s7, s2, 0
	v_writelane_b32 v253, s6, 52
	v_mov_b32_e32 v183, 0x3a800000
	v_mov_b32_e32 v184, 0x7cf
	v_writelane_b32 v253, s7, 53
	s_add_u32 s6, s1, 0x8000
	s_addc_u32 s7, s2, 0
	v_writelane_b32 v253, s6, 54
	s_movk_i32 s1, 0x3ff
	v_and_or_b32 v0, v0, s1, v135
	v_writelane_b32 v253, s7, 55
	v_writelane_b32 v253, s4, 56
	v_writelane_b32 v253, s8, 57
	s_cmp_lt_i32 s4, 0
	s_mul_i32 s1, s4, 0x81
	v_writelane_b32 v254, s15, 0
	v_writelane_b32 v254, s16, 1
	v_writelane_b32 v254, s17, 2
	v_writelane_b32 v254, s18, 3
	s_cselect_b32 s0, s1, s0
	v_writelane_b32 v254, s19, 4
	s_add_i32 s0, s0, s3
	v_writelane_b32 v254, s20, 5
	s_ashr_i32 s1, s0, 31
	v_writelane_b32 v254, s21, 6
	s_lshr_b32 s1, s1, 28
	v_writelane_b32 v254, s22, 7
	s_add_i32 s1, s0, s1
	v_writelane_b32 v254, s23, 8
	s_and_b32 s2, s1, -16
	v_writelane_b32 v254, s3, 9
	s_sub_i32 s6, s0, s2
	s_ashr_i32 s2, s1, 4
	s_ashr_i32 s0, s1, 7
	v_writelane_b32 v254, s2, 10
	s_mov_b32 s4, s6
	s_ashr_i32 s1, s0, 31
	s_lshl_b32 s2, s2, 20
	s_ashr_i32 s7, s6, 31
	v_writelane_b32 v254, s4, 11
	s_lshl_b64 s[0:1], s[0:1], 23
	s_and_b32 s2, s2, 0x700000
	v_writelane_b32 v254, s5, 12
	s_lshl_b64 s[4:5], s[6:7], 19
	s_add_u32 s0, s22, s0
	s_addc_u32 s1, s23, s1
	v_writelane_b32 v254, s4, 13
	s_add_u32 s0, s0, s2
	s_addc_u32 s1, s1, 0
	v_writelane_b32 v254, s5, 14
	s_add_u32 s2, s0, 0x80000
	v_writelane_b32 v254, s0, 15
	s_addc_u32 s3, s1, 0
	v_writelane_b32 v253, s9, 58
	v_writelane_b32 v254, s1, 16
	v_writelane_b32 v254, s2, 17
	s_add_i32 s0, 0, 0x2940
	v_writelane_b32 v253, s10, 59
	v_writelane_b32 v254, s3, 18
	v_writelane_b32 v254, s0, 19
	s_add_i32 s0, 0, 0x2b40
	v_writelane_b32 v254, s0, 20
	s_add_i32 s0, 0, 0x23f20
	v_writelane_b32 v254, s0, 21
	s_add_i32 s0, 0, 0x23f24
	v_writelane_b32 v254, s0, 22
	v_cmp_eq_u32_e64 s[0:1], 0, v0
	v_writelane_b32 v253, s11, 60
	v_writelane_b32 v253, s12, 61
	v_writelane_b32 v254, s0, 23
	v_writelane_b32 v253, s13, 62
	v_writelane_b32 v253, s14, 63
	v_writelane_b32 v254, s1, 24
	s_load_dwordx2 s[0:1], s[80:81], 0x38
	v_mov_b32_e32 v185, 0x1580
	s_mov_b32 s61, 0x10000
	s_mov_b32 s37, 0x18000
	s_mov_b32 s57, 0x8000
	s_waitcnt lgkmcnt(0)
; __device__ __forceinline__ unsigned xb_xcc_id() { return (unsigned)__builtin_amdgcn_s_getreg((3 << 11) | 20) & 0xFu; }
; __global__ void __launch_bounds__(NWAVES * 64, 2) hybrid_fwd(Args args) {
;     ...
;     (void)xcd_barrier_post((unsigned*)(args.ws + WS_CTL), MISC + 8);
;     if (threadIdx.x == 0) atomicOr((unsigned*)(args.ws + WS_CTL) + GB_MASK(blockIdx.x & 7), 1u << xb_xcc_id());
;     unsigned gbn = 0;
	v_writelane_b32 v254, s0, 25
	s_mov_b32 s91, 0xffff0000
	s_mov_b32 s58, 0x20000
	v_writelane_b32 v254, s1, 26
	s_load_dwordx4 s[0:3], s[80:81], 0x20
	s_mov_b32 s59, 0x30000
	s_movk_i32 s90, 0x7fff
	s_movk_i32 s78, 0x1080
	s_mov_b32 s79, 0x800000
	s_waitcnt lgkmcnt(0)
	v_writelane_b32 v254, s0, 27
	s_movk_i32 s33, 0x84
	s_mov_b32 s69, 0
	v_writelane_b32 v254, s1, 28
	v_writelane_b32 v254, s2, 29
	v_writelane_b32 v254, s3, 30
	s_load_dwordx8 s[0:7], s[80:81], 0x0
	s_mov_b32 s85, 0
	s_mov_b64 s[76:77], 0x80
	s_mov_b32 s20, 0x3c800000
	s_waitcnt lgkmcnt(0)
	v_writelane_b32 v254, s0, 31
	s_nop 1
	v_writelane_b32 v254, s1, 32
	v_writelane_b32 v254, s2, 33
	v_writelane_b32 v254, s3, 34
	v_writelane_b32 v254, s4, 35
	v_writelane_b32 v254, s5, 36
	v_writelane_b32 v254, s6, 37
	v_writelane_b32 v254, s7, 38
	s_load_dwordx16 s[0:15], s[80:81], 0x48
	s_waitcnt lgkmcnt(0)
	v_writelane_b32 v254, s0, 39
	s_nop 1
	v_writelane_b32 v254, s1, 40
	v_writelane_b32 v254, s2, 41
	v_writelane_b32 v254, s3, 42
	v_writelane_b32 v254, s4, 43
	v_writelane_b32 v254, s5, 44
	v_writelane_b32 v254, s6, 45
	v_writelane_b32 v254, s7, 46
	v_writelane_b32 v254, s8, 47
	v_writelane_b32 v254, s9, 48
	v_writelane_b32 v254, s10, 49
	v_writelane_b32 v254, s11, 50
	v_writelane_b32 v254, s12, 51
	v_writelane_b32 v254, s13, 52
	v_writelane_b32 v254, s14, 53
	v_writelane_b32 v254, s15, 54
	v_writelane_b32 v254, s56, 55
	v_writelane_b32 v254, s80, 56
	s_nop 1
	v_writelane_b32 v254, s81, 57
	s_mov_b32 s98, 0
	s_mov_b32 s99, 0
	s_mov_b32 s101, 0
	s_branch .LBB0_13

; __global__ void __launch_bounds__(NWAVES * 64, 2) hybrid_fwd(Args args) {
;     ...
;                 for (int j = bx; j < (MS / 64) * (FF / 64); j += G) small_gemm_tile<4, 1, DM>(lds, (const bf16*)args.out, (const bf16*)(wl + W_UP), (bf16*)(ws + WS_H), FP, 2 * DM, DM + WPAD, (const float*)(ws + WS_RS), MP + (j & 7) * 64, SMALL_TN(j, FF / 64) * 64, tid);
.Lws_done_up:
	s_cmp_eq_u32 s98, 1
	s_cbranch_scc1 .Lws_nc_up
	buffer_inv sc1
	s_waitcnt vmcnt(0)

; __device__ __forceinline__ void ew_load(EwRow& r, const bf16* __restrict__ xrow16, const bf16* __restrict__ orow, int lane) {
;     const v4u* xr = (const v4u*)xrow16 + lane; const v4u* orr = (const v4u*)orow + lane;
; #pragma unroll
;     for (int j = 0; j < 2; ++j) { r.x[j] = xr[64 * j]; r.o[j] = orr[64 * j]; }
; }
; __global__ void __launch_bounds__(NWAVES * 64, 2) hybrid_fwd(Args args) {
;     ...
;                   if (nk > 0) { EwRow r0, r1, r2;
;                     { const int ma = EW_ROW(0); ew_load(r0, X16 + (size_t)ma * 2 * DM, OB + (size_t)ma * OP, lane); }
;                     { const int kb = 1 < nk ? 1 : 0; const int mb = EW_ROW(kb); ew_load(r1, X16 + (size_t)mb * 2 * DM, OB + (size_t)mb * OP, lane); }
.LBB0_425:
	s_add_i32 s8, s38, -15
	s_cmp_lg_u32 s86, 6
	s_cselect_b64 s[4:5], -1, 0
	s_cmp_lt_u32 s8, -7
	s_cselect_b64 s[8:9], -1, 0
	s_ashr_i32 s10, s10, 5
	s_or_b64 s[4:5], s[8:9], s[4:5]
	s_lshl_b32 s24, s10, 11
	s_xor_b64 s[8:9], s[4:5], -1
	s_add_i32 s18, s12, s24
	s_and_b64 s[14:15], s[6:7], exec
	s_cselect_b32 s14, s18, s2
	s_ashr_i32 s15, s14, 31
	v_readlane_b32 s40, v253, 57
	s_lshl_b64 s[22:23], s[14:15], 12
	v_readlane_b32 s54, v254, 7
	v_readlane_b32 s55, v254, 8
	s_add_u32 s22, s54, s22
	s_addc_u32 s23, s55, s23
	s_lshl_b64 s[14:15], s[14:15], 11
	v_readlane_b32 s26, v253, 32
	v_readlane_b32 s27, v253, 33
	s_add_u32 s14, s26, s14
	s_addc_u32 s15, s27, s15
	v_lshlrev_b32_e32 v128, 4, v134
	s_cmp_eq_u32 s17, 1
	global_load_dwordx4 v[56:59], v128, s[22:23] sc1
	global_load_dwordx4 v[48:51], v128, s[22:23] offset:1024 sc1
	global_load_dwordx4 v[60:63], v128, s[14:15] sc1
	global_load_dwordx4 v[52:55], v128, s[14:15] offset:1024 sc1
	s_cselect_b32 s13, 0, s16
	s_cselect_b32 s14, 0, 0x100
	s_add_i32 s13, s13, s2
	s_add_i32 s14, s18, s14
	s_and_b64 s[6:7], s[6:7], exec
	s_cselect_b32 s6, s14, s13
	s_lshl_b32 s7, s10, 6
	s_add_i32 s21, s12, s7
	s_ashr_i32 s7, s6, 31
	s_lshl_b64 s[12:13], s[6:7], 11
	s_add_u32 s12, s26, s12
	s_addc_u32 s13, s27, s13
	s_lshl_b64 s[6:7], s[6:7], 12
	s_add_u32 s6, s54, s6
	s_addc_u32 s7, s55, s7
	global_load_dwordx4 v[36:39], v128, s[12:13] offset:1024 sc1
	global_load_dwordx4 v[44:47], v128, s[12:13] sc1
	global_load_dwordx4 v[40:43], v128, s[6:7] offset:1024 sc1
	global_load_dwordx4 v[32:35], v128, s[6:7] sc1
	v_lshlrev_b32_e32 v16, 1, v134
	s_add_i32 s10, s70, s24
	s_mov_b32 s19, 0
	v_lshl_add_u64 v[64:65], s[54:55], 0, v[128:129]
	v_lshl_add_u64 v[66:67], s[26:27], 0, v[128:129]
	s_addk_i32 s21, 0x4000
	v_cmp_eq_u32_e64 s[6:7], 0, v134
	s_add_i32 s22, s10, s11
	v_lshlrev_b32_e32 v68, 4, v16
	v_lshlrev_b32_e32 v69, 4, v134
	v_readlane_b32 s41, v253, 58
	v_readlane_b32 s42, v253, 59
	v_readlane_b32 s43, v253, 60
	v_readlane_b32 s44, v253, 61
	v_readlane_b32 s45, v253, 62
	v_readlane_b32 s46, v253, 63
	v_readlane_b32 s47, v254, 0
	v_readlane_b32 s48, v254, 1
	v_readlane_b32 s49, v254, 2
	v_readlane_b32 s50, v254, 3
	v_readlane_b32 s51, v254, 4
	v_readlane_b32 s52, v254, 5
	v_readlane_b32 s53, v254, 6
	s_branch .LBB0_428

; __global__ void __launch_bounds__(NWAVES * 64, 2) hybrid_fwd(Args args) {
;     ...
;                         { const int kc = k + 2 < nk ? k + 2 : k; const int mc = EW_ROW(kc); ew_load(r2, X16 + (size_t)mc * 2 * DM, OB + (size_t)mc * OP, lane); }
.LBB0_433:
	s_ashr_i32 s11, s10, 31
	s_lshl_b64 s[12:13], s[10:11], 12
	s_lshl_b64 s[10:11], s[10:11], 11
	v_lshl_add_u64 v[36:37], v[64:65], 0, s[12:13]
	v_lshl_add_u64 v[38:39], v[66:67], 0, s[10:11]
	global_load_dwordx4 v[32:35], v[36:37], off sc1
	global_load_dwordx4 v[40:43], v[36:37], off offset:1024 sc1
	global_load_dwordx4 v[44:47], v[38:39], off sc1
	s_nop 0
	global_load_dwordx4 v[36:39], v[38:39], off offset:1024 sc1
	s_mov_b64 s[12:13], -1
	s_and_b64 vcc, exec, s[0:1]
	s_cbranch_vccz .LBB0_435
	s_mul_i32 s10, s19, s16
	s_add_i32 s10, s10, s2
	s_mov_b64 s[12:13], 0

; __device__ __forceinline__ unsigned xb_ld(unsigned* p)              { return __hip_atomic_load(p, __ATOMIC_RELAXED, __HIP_MEMORY_SCOPE_AGENT); }
; __device__ __forceinline__ void group_barrier(unsigned* ctl, int x, unsigned target, bool coloc) {
;     asm volatile("s_waitcnt vmcnt(0)" ::: "memory");
;     __syncthreads();
;     if (threadIdx.x == 0) {
; __global__ void __launch_bounds__(NWAVES * 64, 2) hybrid_fwd(Args args) {
;     ...
;             else if (local) { unsigned* ctl = (unsigned*)(args.ws + WS_CTL); const int x = blockIdx.x & 7; ++gbn;
;                 const unsigned mk = xb_ld(&ctl[GB_MASK(x)]); group_barrier(ctl, x, 32u * gbn, (mk & (mk - 1u)) == 0u && mk != 0u); }
.Lgb_nomask:
	s_waitcnt vmcnt(0)
	s_cmp_lg_u32 s69, 0
	s_cbranch_scc1 .Lgb_allknown
	v_bcnt_u32_b32 v1, v0, 0
	s_nop 0
	v_readfirstlane_b32 s98, v1
.Lgb_allknown:
	s_barrier
	s_mov_b64 s[0:1], exec
	v_readlane_b32 s4, v253, 0
	v_readlane_b32 s5, v253, 1
	s_and_b64 s[4:5], s[0:1], s[4:5]
	s_mov_b64 exec, s[4:5]
	s_cbranch_execz .LBB0_732
	s_cmp_lg_u32 s69, 0
	s_cbranch_scc1 .Lgb_cached
	s_waitcnt vmcnt(0)
	v_bcnt_u32_b32 v0, v0, 0
	v_cmp_eq_u32_e32 vcc, 1, v0
	s_mov_b32 s98, 1
	s_cbranch_vccnz .LBB0_705
	s_mov_b32 s98, 0
	s_branch .Lgb_wb

; __device__ __forceinline__ unsigned xb_ld(unsigned* p)              { return __hip_atomic_load(p, __ATOMIC_RELAXED, __HIP_MEMORY_SCOPE_AGENT); }
; __device__ __forceinline__ unsigned xb_add(unsigned* p, unsigned v) { return __hip_atomic_fetch_add(p, v, __ATOMIC_RELAXED, __HIP_MEMORY_SCOPE_AGENT); }
; #define XB_SPIN(cond, bar) do { unsigned _sp = 0; while (cond) { __builtin_amdgcn_s_sleep(1); \
;     if ((++_sp & 255u) == 0u) { if (xb_ld(&(bar)[XB_TMO])) break; if (_sp > XB_SPIN_CAP) { atomicAdd(&(bar)[XB_TMO], 1u); break; } } } } while (0)
; __device__ __forceinline__ void group_barrier(unsigned* ctl, int x, unsigned target, bool coloc) {
;     ...
;         if (!coloc) { __builtin_amdgcn_fence(__ATOMIC_RELEASE, "agent"); asm volatile("s_waitcnt vmcnt(0)" ::: "memory"); }
;         (void)xb_add(&ctl[GB_CNT(x)], 1u);
;         XB_SPIN(xb_ld(&ctl[GB_CNT(x)]) < target, ctl);
;         __builtin_amdgcn_fence(__ATOMIC_ACQUIRE, "agent");
;         asm volatile("s_waitcnt vmcnt(0)" ::: "memory");
.LBB0_707:
	s_or_b64 exec, exec, s[4:5]
	s_cmp_eq_u32 s98, 1
	s_cbranch_scc0 .Lgb_noearly
	s_cmp_eq_u32 s2, 4
	s_cbranch_scc1 .Lgb_noearly
	s_cmp_eq_u32 s2, 7
	s_cbranch_scc1 .Lgb_noearly
	s_cmp_eq_u32 s2, 11
	s_cbranch_scc1 .Lgb_noearly
	s_cmp_eq_u32 s2, 14
	s_cbranch_scc1 .Lgb_noearly
	buffer_inv sc1
.Lgb_noearly:
	v_readlane_b32 s4, v253, 54
	v_readlane_b32 s5, v253, 55
	s_lshl_b32 s3, s10, 5
	s_nop 3
	global_load_dword v0, v129, s[4:5] sc1
	s_waitcnt vmcnt(0)
	v_cmp_le_u32_e32 vcc, s3, v0
	s_cbranch_vccnz .LBB0_731
	s_mov_b32 s11, 1
	s_branch .LBB0_710

; __device__ __forceinline__ unsigned xb_ld(unsigned* p)              { return __hip_atomic_load(p, __ATOMIC_RELAXED, __HIP_MEMORY_SCOPE_AGENT); }
; #define XB_SPIN(cond, bar) do { unsigned _sp = 0; while (cond) { __builtin_amdgcn_s_sleep(1); \
;     if ((++_sp & 255u) == 0u) { if (xb_ld(&(bar)[XB_TMO])) break; if (_sp > XB_SPIN_CAP) { atomicAdd(&(bar)[XB_TMO], 1u); break; } } } } while (0)
; __device__ __forceinline__ void group_barrier(unsigned* ctl, int x, unsigned target, bool coloc) {
;     ...
;         XB_SPIN(xb_ld(&ctl[GB_CNT(x)]) < target, ctl);
;         __builtin_amdgcn_fence(__ATOMIC_ACQUIRE, "agent");
;         asm volatile("s_waitcnt vmcnt(0)" ::: "memory");
;     }
;     __syncthreads();
.LBB0_731:
	s_waitcnt vmcnt(0)
	s_cmp_eq_u32 s98, 1
	s_cbranch_scc1 .Lgb_c731
	buffer_inv sc1
.Lgb_c731:
	s_waitcnt vmcnt(0)
.LBB0_732:
	s_or_b64 exec, exec, s[0:1]
	s_barrier
	s_cbranch_execnz .LBB0_11
	s_branch .LBB0_718
